# attn scheduling only (deep LDS prefetch QK/PV, QK prio 2, group-B prefetch after barrier) on original K/V layouts
# speedup vs baseline: 1.5028x; 1.0017x over previous
; #define MFMA(a, b, c) __builtin_amdgcn_mfma_f32_32x32x16_bf16((a), (b), (c), 0, 0, 0)
; #define ATT_BAR() do { asm volatile("s_waitcnt lgkmcnt(0)" ::: "memory"); __builtin_amdgcn_s_barrier(); asm volatile("" ::: "memory"); } while (0)
; DI void attn_phase(const Params& p, const u16* proj, const char* prep, u16* obuf, char* smem) {
;     ...
;       if (grpB && kt + 1 < nt) { sstore((kt + 1) & 1); if (kt + 2 < nt) gload(kt + 2); }
;       ATT_BAR();
;       __builtin_amdgcn_s_setprio(1);
; #pragma unroll
;       for (int kti = 0; kti < 2; ++kti) {
;         {
;           const bf16x8 pf = packacc<0>(st[kti]);
; #pragma unroll
;           for (int vt = 0; vt < 4; ++vt) {
;             O[vt] = MFMA(ld16(Vt + ((vh * 4 + vt) * 32 + l31) * 72 + kti * 32 + 8 * hh), pf, O[vt]);
;           }
;         }
;         {
;           const bf16x8 pf = packacc<1>(st[kti]);
; #pragma unroll
;           for (int vt = 0; vt < 4; ++vt) {
;             O[vt] = MFMA(ld16(Vt + ((vh * 4 + vt) * 32 + l31) * 72 + kti * 32 + 16 + 8 * hh), pf, O[vt]);
;           }
;         }
;       }
;       __builtin_amdgcn_s_setprio(0);
;       if (!grpB && kt + 1 < nt) { sstore((kt + 1) & 1); if (kt + 2 < nt) gload(kt + 2); }
.LBB0_1040:
	s_waitcnt lgkmcnt(0)
	s_barrier
	s_andn2_b64 vcc, exec, s[76:77]
	s_cbranch_vccnz .Lskip_gl_b
	s_add_i32 s13, s67, 2
	s_cmp_ge_i32 s13, s65
	s_cbranch_scc1 .Lskip_gl_b
	v_add_u32_e32 v74, s78, v169
	v_mad_u64_u32 v[74:75], s[14:15], s86, v74, 0
	v_lshlrev_b64 v[74:75], 1, v[74:75]
	v_lshl_add_u64 v[76:77], v[192:193], 0, v[74:75]
	s_lshl_b64 s[14:15], s[78:79], 1
	v_lshl_add_u64 v[74:75], v[196:197], 0, v[74:75]
	global_load_dwordx4 v[128:131], v[76:77], off
	global_load_dwordx4 v[144:147], v[74:75], off
	v_lshl_add_u64 v[76:77], v[184:185], 0, s[14:15]
	v_lshl_add_u64 v[74:75], v[188:189], 0, s[14:15]
	global_load_dwordx4 v[132:135], v[76:77], off
	global_load_dwordx4 v[148:151], v[74:75], off
	v_add_u32_e32 v76, s78, v173
	v_add_u32_e32 v74, s78, v200
	v_mad_u64_u32 v[76:77], s[16:17], s86, v76, 0
	v_mad_u64_u32 v[74:75], s[16:17], s86, v74, 0
	v_lshl_add_u64 v[76:77], v[76:77], 1, v[194:195]
	v_lshl_add_u64 v[74:75], v[74:75], 1, v[198:199]
	global_load_dwordx4 v[136:139], v[76:77], off
	global_load_dwordx4 v[152:155], v[74:75], off
	v_lshl_add_u64 v[76:77], v[186:187], 0, s[14:15]
	v_lshl_add_u64 v[74:75], v[190:191], 0, s[14:15]
	global_load_dwordx4 v[140:143], v[76:77], off
	global_load_dwordx4 v[156:159], v[74:75], off
.Lskip_gl_b:
	s_setprio 1
	v_add_u32_e32 v233, v233, v226
	ds_read_b128 v[244:247], v233 offset:34816
	v_cvt_pk_bf16_f32 v74, v235, v236
	v_cvt_pk_bf16_f32 v75, v237, v238
	v_cvt_pk_bf16_f32 v76, v239, v240
	v_cvt_pk_bf16_f32 v77, v241, v242
	ds_read_b128 v[236:239], v233 offset:39424
	ds_read_b128 v[240:243], v233 offset:44032
	v_cvt_pk_bf16_f32 v80, v80, v81
	v_cvt_pk_bf16_f32 v81, v82, v83
	v_cvt_pk_bf16_f32 v82, v84, v85
	v_cvt_pk_bf16_f32 v83, v87, v89
	v_cvt_pk_bf16_f32 v84, v86, v88
	v_cvt_pk_bf16_f32 v85, v90, v91
	v_cvt_pk_bf16_f32 v86, v92, v93
	v_cvt_pk_bf16_f32 v87, v94, v95
	ds_read_b128 v[88:91], v233 offset:48640
	ds_read_b128 v[92:95], v233 offset:34848
	v_cvt_pk_bf16_f32 v66, v66, v67
	v_cvt_pk_bf16_f32 v67, v68, v69
	v_cvt_pk_bf16_f32 v68, v70, v71
	v_cvt_pk_bf16_f32 v69, v72, v73
	ds_read_b128 v[70:73], v233 offset:39456
	s_waitcnt lgkmcnt(5)
	v_mfma_f32_32x32x16_bf16 v[48:63], v[244:247], v[74:77], v[48:63]
	ds_read_b128 v[244:247], v233 offset:44064
	s_waitcnt lgkmcnt(5)
	v_mfma_f32_32x32x16_bf16 v[32:47], v[236:239], v[74:77], v[32:47]
	ds_read_b128 v[236:239], v233 offset:48672
	s_waitcnt lgkmcnt(5)
	v_mfma_f32_32x32x16_bf16 v[16:31], v[240:243], v[74:77], v[16:31]
	ds_read_b128 v[240:243], v233 offset:34880
	s_waitcnt lgkmcnt(5)
	v_mfma_f32_32x32x16_bf16 v[0:15], v[88:91], v[74:77], v[0:15]
	ds_read_b128 v[88:91], v233 offset:39488
	s_waitcnt lgkmcnt(5)
	v_mfma_f32_32x32x16_bf16 v[48:63], v[92:95], v[80:83], v[48:63]
	ds_read_b128 v[92:95], v233 offset:44096
	s_waitcnt lgkmcnt(5)
	v_mfma_f32_32x32x16_bf16 v[32:47], v[70:73], v[80:83], v[32:47]
	ds_read_b128 v[70:73], v233 offset:48704
	s_waitcnt lgkmcnt(5)
	v_mfma_f32_32x32x16_bf16 v[16:31], v[244:247], v[80:83], v[16:31]
	ds_read_b128 v[244:247], v233 offset:34912
	s_waitcnt lgkmcnt(5)
	v_mfma_f32_32x32x16_bf16 v[0:15], v[236:239], v[80:83], v[0:15]
	ds_read_b128 v[236:239], v233 offset:39520
	s_waitcnt lgkmcnt(5)
	v_mfma_f32_32x32x16_bf16 v[48:63], v[240:243], v[84:87], v[48:63]
	ds_read_b128 v[240:243], v233 offset:44128
	s_waitcnt lgkmcnt(5)
	v_mfma_f32_32x32x16_bf16 v[32:47], v[88:91], v[84:87], v[32:47]
	ds_read_b128 v[88:91], v233 offset:48736
	s_waitcnt lgkmcnt(5)
	v_mfma_f32_32x32x16_bf16 v[16:31], v[92:95], v[84:87], v[16:31]
	s_waitcnt lgkmcnt(4)
	v_mfma_f32_32x32x16_bf16 v[0:15], v[70:73], v[84:87], v[0:15]
	s_waitcnt lgkmcnt(3)
	v_mfma_f32_32x32x16_bf16 v[48:63], v[244:247], v[66:69], v[48:63]
	s_waitcnt lgkmcnt(2)
	v_mfma_f32_32x32x16_bf16 v[32:47], v[236:239], v[66:69], v[32:47]
	s_waitcnt lgkmcnt(1)
	v_mfma_f32_32x32x16_bf16 v[16:31], v[240:243], v[66:69], v[16:31]
	s_waitcnt lgkmcnt(0)
	v_mfma_f32_32x32x16_bf16 v[0:15], v[88:91], v[66:69], v[0:15]
	s_setprio 0
	s_and_b64 s[10:11], s[72:73], s[10:11]
	s_andn2_b64 vcc, exec, s[10:11]
	s_cbranch_vccnz .LBB0_1043
	s_bitcmp1_b32 s12, 0
	s_cselect_b32 s10, 0x11800, 0
	s_add_i32 s10, s10, 0
	v_add3_u32 v66, s10, v201, v162
	s_waitcnt vmcnt(7)
	ds_write_b128 v66, v[128:131]
	v_add3_u32 v66, s10, v203, v182
	s_waitcnt vmcnt(5)
	ds_write_b128 v66, v[132:135] offset:34816
	v_add3_u32 v66, s10, v205, v162
	s_waitcnt vmcnt(3)
	ds_write_b128 v66, v[136:139]
	v_add3_u32 v66, s10, v207, v182
	s_waitcnt vmcnt(1)
	ds_write_b128 v66, v[140:143] offset:34816
	v_add3_u32 v66, s10, v211, v162
	ds_write_b128 v66, v[144:147]
	v_add3_u32 v66, s10, v213, v182
	ds_write_b128 v66, v[148:151] offset:34816
	v_add3_u32 v66, s10, v215, v162
	ds_write_b128 v66, v[152:155]
	v_add3_u32 v66, s10, v217, v182
	s_add_i32 s10, s67, 2
	s_cmp_ge_i32 s10, s65
	s_waitcnt vmcnt(0)
	ds_write_b128 v66, v[156:159] offset:34816
	s_cbranch_scc1 .LBB0_1043
	v_add_u32_e32 v66, s78, v169
	v_mad_u64_u32 v[66:67], s[10:11], s86, v66, 0
	v_lshlrev_b64 v[66:67], 1, v[66:67]
	v_lshl_add_u64 v[68:69], v[192:193], 0, v[66:67]
	s_lshl_b64 s[10:11], s[78:79], 1
	v_lshl_add_u64 v[66:67], v[196:197], 0, v[66:67]
	global_load_dwordx4 v[128:131], v[68:69], off
	global_load_dwordx4 v[144:147], v[66:67], off
	v_lshl_add_u64 v[68:69], v[184:185], 0, s[10:11]
	v_lshl_add_u64 v[66:67], v[188:189], 0, s[10:11]
	global_load_dwordx4 v[132:135], v[68:69], off
	global_load_dwordx4 v[148:151], v[66:67], off
	v_add_u32_e32 v68, s78, v173
	v_add_u32_e32 v66, s78, v200
	v_mad_u64_u32 v[68:69], s[14:15], s86, v68, 0
	v_mad_u64_u32 v[66:67], s[14:15], s86, v66, 0
	v_lshl_add_u64 v[68:69], v[68:69], 1, v[194:195]
	v_lshl_add_u64 v[66:67], v[66:67], 1, v[198:199]
	global_load_dwordx4 v[136:139], v[68:69], off
	global_load_dwordx4 v[152:155], v[66:67], off
	v_lshl_add_u64 v[68:69], v[186:187], 0, s[10:11]
	v_lshl_add_u64 v[66:67], v[190:191], 0, s[10:11]
	global_load_dwordx4 v[140:143], v[68:69], off
	global_load_dwordx4 v[156:159], v[66:67], off
